# SiLU table build in phase 0: loads batched 22 at a time instead of 66 serialized round trips; on top of v37
# speedup vs baseline: 1.0188x; 1.0022x over previous
; #define LAS __attribute__((address_space(3)))
; __device__ __forceinline__ float fast_rcp(float x) { return __builtin_amdgcn_rcpf(x); }
; __device__ __forceinline__ float fast_exp2(float x) { return __builtin_amdgcn_exp2f(x); }
; __device__ __forceinline__ float sigmoidf_(float x) { return fast_rcp(1.0f + fast_exp2(-x * LOG2E)); }
; __device__ __forceinline__ float siluf_(float x) { return x * sigmoidf_(x); }
; __device__ void phase_setup(const Params& p, LAS unsigned char* lds) {
;     ...
;         LAS float* sc = (LAS float*)lds;
;         __syncthreads();
;         for (int i = tid; i < 33 * D; i += 512) { const int r = i >> 10, k = i & 1023; const float v = (r < 32) ? p.in[I_C][r * D + k] : p.in[I_CCTX][k]; sc[i] = siluf_(v); }
;         __syncthreads();
.LBB0_457:
	s_mov_b64 s[6:7], 0x800
	v_lshlrev_b32_e32 v32, 2, v2
	global_load_dword v10, v[4:5], off
	v_lshl_add_u64 v[4:5], v[4:5], 0, s[6:7]
	global_load_dword v11, v[4:5], off
	v_lshl_add_u64 v[4:5], v[4:5], 0, s[6:7]
	global_load_dword v12, v[4:5], off
	v_lshl_add_u64 v[4:5], v[4:5], 0, s[6:7]
	global_load_dword v13, v[4:5], off
	v_lshl_add_u64 v[4:5], v[4:5], 0, s[6:7]
	global_load_dword v14, v[4:5], off
	v_lshl_add_u64 v[4:5], v[4:5], 0, s[6:7]
	global_load_dword v15, v[4:5], off
	v_lshl_add_u64 v[4:5], v[4:5], 0, s[6:7]
	global_load_dword v16, v[4:5], off
	v_lshl_add_u64 v[4:5], v[4:5], 0, s[6:7]
	global_load_dword v17, v[4:5], off
	v_lshl_add_u64 v[4:5], v[4:5], 0, s[6:7]
	global_load_dword v18, v[4:5], off
	v_lshl_add_u64 v[4:5], v[4:5], 0, s[6:7]
	global_load_dword v19, v[4:5], off
	v_lshl_add_u64 v[4:5], v[4:5], 0, s[6:7]
	global_load_dword v20, v[4:5], off
	v_lshl_add_u64 v[4:5], v[4:5], 0, s[6:7]
	global_load_dword v21, v[4:5], off
	v_lshl_add_u64 v[4:5], v[4:5], 0, s[6:7]
	global_load_dword v22, v[4:5], off
	v_lshl_add_u64 v[4:5], v[4:5], 0, s[6:7]
	global_load_dword v23, v[4:5], off
	v_lshl_add_u64 v[4:5], v[4:5], 0, s[6:7]
	global_load_dword v24, v[4:5], off
	v_lshl_add_u64 v[4:5], v[4:5], 0, s[6:7]
	global_load_dword v25, v[4:5], off
	v_lshl_add_u64 v[4:5], v[4:5], 0, s[6:7]
	global_load_dword v26, v[4:5], off
	v_lshl_add_u64 v[4:5], v[4:5], 0, s[6:7]
	global_load_dword v27, v[4:5], off
	v_lshl_add_u64 v[4:5], v[4:5], 0, s[6:7]
	global_load_dword v28, v[4:5], off
	v_lshl_add_u64 v[4:5], v[4:5], 0, s[6:7]
	global_load_dword v29, v[4:5], off
	v_lshl_add_u64 v[4:5], v[4:5], 0, s[6:7]
	global_load_dword v30, v[4:5], off
	v_lshl_add_u64 v[4:5], v[4:5], 0, s[6:7]
	global_load_dword v31, v[4:5], off
	v_lshl_add_u64 v[4:5], v[4:5], 0, s[6:7]
	s_waitcnt vmcnt(0)
	v_mul_f32_e32 v40, 0xbfb8aa3b, v10
	v_exp_f32_e32 v40, v40
	s_nop 0
	v_add_f32_e32 v40, 1.0, v40
	v_rcp_f32_e32 v40, v40
	s_nop 0
	v_mul_f32_e32 v10, v10, v40
	ds_write_b32 v6, v10
	v_add_u32_e32 v6, 0x800, v6
	v_mul_f32_e32 v40, 0xbfb8aa3b, v11
	v_exp_f32_e32 v40, v40
	s_nop 0
	v_add_f32_e32 v40, 1.0, v40
	v_rcp_f32_e32 v40, v40
	s_nop 0
	v_mul_f32_e32 v11, v11, v40
	ds_write_b32 v6, v11
	v_add_u32_e32 v6, 0x800, v6
	v_mul_f32_e32 v40, 0xbfb8aa3b, v12
	v_exp_f32_e32 v40, v40
	s_nop 0
	v_add_f32_e32 v40, 1.0, v40
	v_rcp_f32_e32 v40, v40
	s_nop 0
	v_mul_f32_e32 v12, v12, v40
	ds_write_b32 v6, v12
	v_add_u32_e32 v6, 0x800, v6
	v_mul_f32_e32 v40, 0xbfb8aa3b, v13
	v_exp_f32_e32 v40, v40
	s_nop 0
	v_add_f32_e32 v40, 1.0, v40
	v_rcp_f32_e32 v40, v40
	s_nop 0
	v_mul_f32_e32 v13, v13, v40
	ds_write_b32 v6, v13
	v_add_u32_e32 v6, 0x800, v6
	v_mul_f32_e32 v40, 0xbfb8aa3b, v14
	v_exp_f32_e32 v40, v40
	s_nop 0
	v_add_f32_e32 v40, 1.0, v40
	v_rcp_f32_e32 v40, v40
	s_nop 0
	v_mul_f32_e32 v14, v14, v40
	ds_write_b32 v6, v14
	v_add_u32_e32 v6, 0x800, v6
	v_mul_f32_e32 v40, 0xbfb8aa3b, v15
	v_exp_f32_e32 v40, v40
	s_nop 0
	v_add_f32_e32 v40, 1.0, v40
	v_rcp_f32_e32 v40, v40
	s_nop 0
	v_mul_f32_e32 v15, v15, v40
	ds_write_b32 v6, v15
	v_add_u32_e32 v6, 0x800, v6
	v_mul_f32_e32 v40, 0xbfb8aa3b, v16
	v_exp_f32_e32 v40, v40
	s_nop 0
	v_add_f32_e32 v40, 1.0, v40
	v_rcp_f32_e32 v40, v40
	s_nop 0
	v_mul_f32_e32 v16, v16, v40
	ds_write_b32 v6, v16
	v_add_u32_e32 v6, 0x800, v6
	v_mul_f32_e32 v40, 0xbfb8aa3b, v17
	v_exp_f32_e32 v40, v40
	s_nop 0
	v_add_f32_e32 v40, 1.0, v40
	v_rcp_f32_e32 v40, v40
	s_nop 0
	v_mul_f32_e32 v17, v17, v40
	ds_write_b32 v6, v17
	v_add_u32_e32 v6, 0x800, v6
	v_mul_f32_e32 v40, 0xbfb8aa3b, v18
	v_exp_f32_e32 v40, v40
	s_nop 0
	v_add_f32_e32 v40, 1.0, v40
	v_rcp_f32_e32 v40, v40
	s_nop 0
	v_mul_f32_e32 v18, v18, v40
	ds_write_b32 v6, v18
	v_add_u32_e32 v6, 0x800, v6
	v_mul_f32_e32 v40, 0xbfb8aa3b, v19
	v_exp_f32_e32 v40, v40
	s_nop 0
	v_add_f32_e32 v40, 1.0, v40
	v_rcp_f32_e32 v40, v40
	s_nop 0
	v_mul_f32_e32 v19, v19, v40
	ds_write_b32 v6, v19
	v_add_u32_e32 v6, 0x800, v6
	v_mul_f32_e32 v40, 0xbfb8aa3b, v20
	v_exp_f32_e32 v40, v40
	s_nop 0
	v_add_f32_e32 v40, 1.0, v40
	v_rcp_f32_e32 v40, v40
	s_nop 0
	v_mul_f32_e32 v20, v20, v40
	ds_write_b32 v6, v20
	v_add_u32_e32 v6, 0x800, v6
	v_mul_f32_e32 v40, 0xbfb8aa3b, v21
	v_exp_f32_e32 v40, v40
	s_nop 0
	v_add_f32_e32 v40, 1.0, v40
	v_rcp_f32_e32 v40, v40
	s_nop 0
	v_mul_f32_e32 v21, v21, v40
	ds_write_b32 v6, v21
	v_add_u32_e32 v6, 0x800, v6
	v_mul_f32_e32 v40, 0xbfb8aa3b, v22
	v_exp_f32_e32 v40, v40
	s_nop 0
	v_add_f32_e32 v40, 1.0, v40
	v_rcp_f32_e32 v40, v40
	s_nop 0
	v_mul_f32_e32 v22, v22, v40
	ds_write_b32 v6, v22
	v_add_u32_e32 v6, 0x800, v6
	v_mul_f32_e32 v40, 0xbfb8aa3b, v23
	v_exp_f32_e32 v40, v40
	s_nop 0
	v_add_f32_e32 v40, 1.0, v40
	v_rcp_f32_e32 v40, v40
	s_nop 0
	v_mul_f32_e32 v23, v23, v40
	ds_write_b32 v6, v23
	v_add_u32_e32 v6, 0x800, v6
	v_mul_f32_e32 v40, 0xbfb8aa3b, v24
	v_exp_f32_e32 v40, v40
	s_nop 0
	v_add_f32_e32 v40, 1.0, v40
	v_rcp_f32_e32 v40, v40
	s_nop 0
	v_mul_f32_e32 v24, v24, v40
	ds_write_b32 v6, v24
	v_add_u32_e32 v6, 0x800, v6
	v_mul_f32_e32 v40, 0xbfb8aa3b, v25
	v_exp_f32_e32 v40, v40
	s_nop 0
	v_add_f32_e32 v40, 1.0, v40
	v_rcp_f32_e32 v40, v40
	s_nop 0
	v_mul_f32_e32 v25, v25, v40
	ds_write_b32 v6, v25
	v_add_u32_e32 v6, 0x800, v6
	v_mul_f32_e32 v40, 0xbfb8aa3b, v26
	v_exp_f32_e32 v40, v40
	s_nop 0
	v_add_f32_e32 v40, 1.0, v40
	v_rcp_f32_e32 v40, v40
	s_nop 0
	v_mul_f32_e32 v26, v26, v40
	ds_write_b32 v6, v26
	v_add_u32_e32 v6, 0x800, v6
	v_mul_f32_e32 v40, 0xbfb8aa3b, v27
	v_exp_f32_e32 v40, v40
	s_nop 0
	v_add_f32_e32 v40, 1.0, v40
	v_rcp_f32_e32 v40, v40
	s_nop 0
	v_mul_f32_e32 v27, v27, v40
	ds_write_b32 v6, v27
	v_add_u32_e32 v6, 0x800, v6
	v_mul_f32_e32 v40, 0xbfb8aa3b, v28
; #define LAS __attribute__((address_space(3)))
; __device__ __forceinline__ float fast_rcp(float x) { return __builtin_amdgcn_rcpf(x); }
; __device__ __forceinline__ float fast_exp2(float x) { return __builtin_amdgcn_exp2f(x); }
; __device__ __forceinline__ float sigmoidf_(float x) { return fast_rcp(1.0f + fast_exp2(-x * LOG2E)); }
; __device__ __forceinline__ float siluf_(float x) { return x * sigmoidf_(x); }
; __device__ void phase_setup(const Params& p, LAS unsigned char* lds) {
;     ...
;         LAS float* sc = (LAS float*)lds;
;         __syncthreads();
;         for (int i = tid; i < 33 * D; i += 512) { const int r = i >> 10, k = i & 1023; const float v = (r < 32) ? p.in[I_C][r * D + k] : p.in[I_CCTX][k]; sc[i] = siluf_(v); }
;         __syncthreads();
	v_exp_f32_e32 v40, v40
	s_nop 0
	v_add_f32_e32 v40, 1.0, v40
	v_rcp_f32_e32 v40, v40
	s_nop 0
	v_mul_f32_e32 v28, v28, v40
	ds_write_b32 v6, v28
	v_add_u32_e32 v6, 0x800, v6
	v_mul_f32_e32 v40, 0xbfb8aa3b, v29
	v_exp_f32_e32 v40, v40
	s_nop 0
	v_add_f32_e32 v40, 1.0, v40
	v_rcp_f32_e32 v40, v40
	s_nop 0
	v_mul_f32_e32 v29, v29, v40
	ds_write_b32 v6, v29
	v_add_u32_e32 v6, 0x800, v6
	v_mul_f32_e32 v40, 0xbfb8aa3b, v30
	v_exp_f32_e32 v40, v40
	s_nop 0
	v_add_f32_e32 v40, 1.0, v40
	v_rcp_f32_e32 v40, v40
	s_nop 0
	v_mul_f32_e32 v30, v30, v40
	ds_write_b32 v6, v30
	v_add_u32_e32 v6, 0x800, v6
	v_mul_f32_e32 v40, 0xbfb8aa3b, v31
	v_exp_f32_e32 v40, v40
	s_nop 0
	v_add_f32_e32 v40, 1.0, v40
	v_rcp_f32_e32 v40, v40
	s_nop 0
	v_mul_f32_e32 v31, v31, v40
	ds_write_b32 v6, v31
	v_add_u32_e32 v6, 0x800, v6
	global_load_dword v10, v[4:5], off
	v_lshl_add_u64 v[4:5], v[4:5], 0, s[6:7]
	global_load_dword v11, v[4:5], off
	v_lshl_add_u64 v[4:5], v[4:5], 0, s[6:7]
	global_load_dword v12, v[4:5], off
	v_lshl_add_u64 v[4:5], v[4:5], 0, s[6:7]
	global_load_dword v13, v[4:5], off
	v_lshl_add_u64 v[4:5], v[4:5], 0, s[6:7]
	global_load_dword v14, v[4:5], off
	v_lshl_add_u64 v[4:5], v[4:5], 0, s[6:7]
	global_load_dword v15, v[4:5], off
	v_lshl_add_u64 v[4:5], v[4:5], 0, s[6:7]
	global_load_dword v16, v[4:5], off
	v_lshl_add_u64 v[4:5], v[4:5], 0, s[6:7]
	global_load_dword v17, v[4:5], off
	v_lshl_add_u64 v[4:5], v[4:5], 0, s[6:7]
	global_load_dword v18, v[4:5], off
	v_lshl_add_u64 v[4:5], v[4:5], 0, s[6:7]
	global_load_dword v19, v[4:5], off
	v_lshl_add_u64 v[4:5], v[4:5], 0, s[6:7]
	global_load_dword v20, v[4:5], off
	v_lshl_add_u64 v[4:5], v[4:5], 0, s[6:7]
	global_load_dword v21, v[4:5], off
	v_lshl_add_u64 v[4:5], v[4:5], 0, s[6:7]
	global_load_dword v22, v[4:5], off
	v_lshl_add_u64 v[4:5], v[4:5], 0, s[6:7]
	global_load_dword v23, v[4:5], off
	v_lshl_add_u64 v[4:5], v[4:5], 0, s[6:7]
	global_load_dword v24, v[4:5], off
	v_lshl_add_u64 v[4:5], v[4:5], 0, s[6:7]
	global_load_dword v25, v[4:5], off
	v_lshl_add_u64 v[4:5], v[4:5], 0, s[6:7]
	global_load_dword v26, v[4:5], off
	v_lshl_add_u64 v[4:5], v[4:5], 0, s[6:7]
	global_load_dword v27, v[4:5], off
	v_lshl_add_u64 v[4:5], v[4:5], 0, s[6:7]
	global_load_dword v28, v[4:5], off
	v_lshl_add_u64 v[4:5], v[4:5], 0, s[6:7]
	global_load_dword v29, v[4:5], off
	v_lshl_add_u64 v[4:5], v[4:5], 0, s[6:7]
	global_load_dword v30, v[4:5], off
	v_lshl_add_u64 v[4:5], v[4:5], 0, s[6:7]
	global_load_dword v31, v[4:5], off
	v_lshl_add_u64 v[4:5], v[4:5], 0, s[6:7]
	s_waitcnt vmcnt(0)
	v_mul_f32_e32 v40, 0xbfb8aa3b, v10
	v_exp_f32_e32 v40, v40
	s_nop 0
	v_add_f32_e32 v40, 1.0, v40
	v_rcp_f32_e32 v40, v40
	s_nop 0
	v_mul_f32_e32 v10, v10, v40
	ds_write_b32 v6, v10
	v_add_u32_e32 v6, 0x800, v6
	v_mul_f32_e32 v40, 0xbfb8aa3b, v11
	v_exp_f32_e32 v40, v40
	s_nop 0
	v_add_f32_e32 v40, 1.0, v40
	v_rcp_f32_e32 v40, v40
	s_nop 0
	v_mul_f32_e32 v11, v11, v40
	ds_write_b32 v6, v11
	v_add_u32_e32 v6, 0x800, v6
	v_mul_f32_e32 v40, 0xbfb8aa3b, v12
	v_exp_f32_e32 v40, v40
	s_nop 0
	v_add_f32_e32 v40, 1.0, v40
	v_rcp_f32_e32 v40, v40
	s_nop 0
	v_mul_f32_e32 v12, v12, v40
	ds_write_b32 v6, v12
	v_add_u32_e32 v6, 0x800, v6
	v_mul_f32_e32 v40, 0xbfb8aa3b, v13
	v_exp_f32_e32 v40, v40
	s_nop 0
	v_add_f32_e32 v40, 1.0, v40
	v_rcp_f32_e32 v40, v40
	s_nop 0
	v_mul_f32_e32 v13, v13, v40
	ds_write_b32 v6, v13
	v_add_u32_e32 v6, 0x800, v6
	v_mul_f32_e32 v40, 0xbfb8aa3b, v14
	v_exp_f32_e32 v40, v40
	s_nop 0
	v_add_f32_e32 v40, 1.0, v40
	v_rcp_f32_e32 v40, v40
	s_nop 0
	v_mul_f32_e32 v14, v14, v40
	ds_write_b32 v6, v14
	v_add_u32_e32 v6, 0x800, v6
	v_mul_f32_e32 v40, 0xbfb8aa3b, v15
	v_exp_f32_e32 v40, v40
	s_nop 0
	v_add_f32_e32 v40, 1.0, v40
	v_rcp_f32_e32 v40, v40
	s_nop 0
	v_mul_f32_e32 v15, v15, v40
	ds_write_b32 v6, v15
	v_add_u32_e32 v6, 0x800, v6
	v_mul_f32_e32 v40, 0xbfb8aa3b, v16
	v_exp_f32_e32 v40, v40
	s_nop 0
	v_add_f32_e32 v40, 1.0, v40
	v_rcp_f32_e32 v40, v40
	s_nop 0
	v_mul_f32_e32 v16, v16, v40
	ds_write_b32 v6, v16
	v_add_u32_e32 v6, 0x800, v6
	v_mul_f32_e32 v40, 0xbfb8aa3b, v17
	v_exp_f32_e32 v40, v40
	s_nop 0
	v_add_f32_e32 v40, 1.0, v40
	v_rcp_f32_e32 v40, v40
	s_nop 0
	v_mul_f32_e32 v17, v17, v40
	ds_write_b32 v6, v17
	v_add_u32_e32 v6, 0x800, v6
	v_mul_f32_e32 v40, 0xbfb8aa3b, v18
	v_exp_f32_e32 v40, v40
	s_nop 0
	v_add_f32_e32 v40, 1.0, v40
	v_rcp_f32_e32 v40, v40
	s_nop 0
	v_mul_f32_e32 v18, v18, v40
	ds_write_b32 v6, v18
	v_add_u32_e32 v6, 0x800, v6
	v_mul_f32_e32 v40, 0xbfb8aa3b, v19
	v_exp_f32_e32 v40, v40
	s_nop 0
	v_add_f32_e32 v40, 1.0, v40
	v_rcp_f32_e32 v40, v40
	s_nop 0
	v_mul_f32_e32 v19, v19, v40
	ds_write_b32 v6, v19
	v_add_u32_e32 v6, 0x800, v6
	v_mul_f32_e32 v40, 0xbfb8aa3b, v20
	v_exp_f32_e32 v40, v40
	s_nop 0
	v_add_f32_e32 v40, 1.0, v40
	v_rcp_f32_e32 v40, v40
	s_nop 0
	v_mul_f32_e32 v20, v20, v40
	ds_write_b32 v6, v20
	v_add_u32_e32 v6, 0x800, v6
	v_mul_f32_e32 v40, 0xbfb8aa3b, v21
	v_exp_f32_e32 v40, v40
	s_nop 0
	v_add_f32_e32 v40, 1.0, v40
	v_rcp_f32_e32 v40, v40
	s_nop 0
	v_mul_f32_e32 v21, v21, v40
	ds_write_b32 v6, v21
	v_add_u32_e32 v6, 0x800, v6
	v_mul_f32_e32 v40, 0xbfb8aa3b, v22
	v_exp_f32_e32 v40, v40
	s_nop 0
	v_add_f32_e32 v40, 1.0, v40
	v_rcp_f32_e32 v40, v40
	s_nop 0
	v_mul_f32_e32 v22, v22, v40
	ds_write_b32 v6, v22
	v_add_u32_e32 v6, 0x800, v6
	v_mul_f32_e32 v40, 0xbfb8aa3b, v23
	v_exp_f32_e32 v40, v40
	s_nop 0
	v_add_f32_e32 v40, 1.0, v40
	v_rcp_f32_e32 v40, v40
	s_nop 0
	v_mul_f32_e32 v23, v23, v40
	ds_write_b32 v6, v23
	v_add_u32_e32 v6, 0x800, v6
	v_mul_f32_e32 v40, 0xbfb8aa3b, v24
	v_exp_f32_e32 v40, v40
	s_nop 0
	v_add_f32_e32 v40, 1.0, v40
	v_rcp_f32_e32 v40, v40
	s_nop 0
; #define LAS __attribute__((address_space(3)))
; __device__ __forceinline__ float fast_rcp(float x) { return __builtin_amdgcn_rcpf(x); }
; __device__ __forceinline__ float fast_exp2(float x) { return __builtin_amdgcn_exp2f(x); }
; __device__ __forceinline__ float sigmoidf_(float x) { return fast_rcp(1.0f + fast_exp2(-x * LOG2E)); }
; __device__ __forceinline__ float siluf_(float x) { return x * sigmoidf_(x); }
; __device__ void phase_setup(const Params& p, LAS unsigned char* lds) {
;     ...
;         LAS float* sc = (LAS float*)lds;
;         __syncthreads();
;         for (int i = tid; i < 33 * D; i += 512) { const int r = i >> 10, k = i & 1023; const float v = (r < 32) ? p.in[I_C][r * D + k] : p.in[I_CCTX][k]; sc[i] = siluf_(v); }
;         __syncthreads();
	v_mul_f32_e32 v24, v24, v40
	ds_write_b32 v6, v24
	v_add_u32_e32 v6, 0x800, v6
	v_mul_f32_e32 v40, 0xbfb8aa3b, v25
	v_exp_f32_e32 v40, v40
	s_nop 0
	v_add_f32_e32 v40, 1.0, v40
	v_rcp_f32_e32 v40, v40
	s_nop 0
	v_mul_f32_e32 v25, v25, v40
	ds_write_b32 v6, v25
	v_add_u32_e32 v6, 0x800, v6
	v_mul_f32_e32 v40, 0xbfb8aa3b, v26
	v_exp_f32_e32 v40, v40
	s_nop 0
	v_add_f32_e32 v40, 1.0, v40
	v_rcp_f32_e32 v40, v40
	s_nop 0
	v_mul_f32_e32 v26, v26, v40
	ds_write_b32 v6, v26
	v_add_u32_e32 v6, 0x800, v6
	v_mul_f32_e32 v40, 0xbfb8aa3b, v27
	v_exp_f32_e32 v40, v40
	s_nop 0
	v_add_f32_e32 v40, 1.0, v40
	v_rcp_f32_e32 v40, v40
	s_nop 0
	v_mul_f32_e32 v27, v27, v40
	ds_write_b32 v6, v27
	v_add_u32_e32 v6, 0x800, v6
	v_mul_f32_e32 v40, 0xbfb8aa3b, v28
	v_exp_f32_e32 v40, v40
	s_nop 0
	v_add_f32_e32 v40, 1.0, v40
	v_rcp_f32_e32 v40, v40
	s_nop 0
	v_mul_f32_e32 v28, v28, v40
	ds_write_b32 v6, v28
	v_add_u32_e32 v6, 0x800, v6
	v_mul_f32_e32 v40, 0xbfb8aa3b, v29
	v_exp_f32_e32 v40, v40
	s_nop 0
	v_add_f32_e32 v40, 1.0, v40
	v_rcp_f32_e32 v40, v40
	s_nop 0
	v_mul_f32_e32 v29, v29, v40
	ds_write_b32 v6, v29
	v_add_u32_e32 v6, 0x800, v6
	v_mul_f32_e32 v40, 0xbfb8aa3b, v30
	v_exp_f32_e32 v40, v40
	s_nop 0
	v_add_f32_e32 v40, 1.0, v40
	v_rcp_f32_e32 v40, v40
	s_nop 0
	v_mul_f32_e32 v30, v30, v40
	ds_write_b32 v6, v30
	v_add_u32_e32 v6, 0x800, v6
	v_mul_f32_e32 v40, 0xbfb8aa3b, v31
	v_exp_f32_e32 v40, v40
	s_nop 0
	v_add_f32_e32 v40, 1.0, v40
	v_rcp_f32_e32 v40, v40
	s_nop 0
	v_mul_f32_e32 v31, v31, v40
	ds_write_b32 v6, v31
	v_add_u32_e32 v6, 0x800, v6
	global_load_dword v10, v[4:5], off
	v_lshl_add_u64 v[4:5], v[4:5], 0, s[6:7]
	global_load_dword v11, v[4:5], off
	v_lshl_add_u64 v[4:5], v[4:5], 0, s[6:7]
	global_load_dword v12, v[4:5], off
	v_lshl_add_u64 v[4:5], v[4:5], 0, s[6:7]
	global_load_dword v13, v[4:5], off
	v_lshl_add_u64 v[4:5], v[4:5], 0, s[6:7]
	global_load_dword v14, v[4:5], off
	v_lshl_add_u64 v[4:5], v[4:5], 0, s[6:7]
	global_load_dword v15, v[4:5], off
	v_lshl_add_u64 v[4:5], v[4:5], 0, s[6:7]
	global_load_dword v16, v[4:5], off
	v_lshl_add_u64 v[4:5], v[4:5], 0, s[6:7]
	global_load_dword v17, v[4:5], off
	v_lshl_add_u64 v[4:5], v[4:5], 0, s[6:7]
	global_load_dword v18, v[4:5], off
	v_lshl_add_u64 v[4:5], v[4:5], 0, s[6:7]
	global_load_dword v19, v[4:5], off
	v_lshl_add_u64 v[4:5], v[4:5], 0, s[6:7]
	global_load_dword v20, v[4:5], off
	v_lshl_add_u64 v[4:5], v[4:5], 0, s[6:7]
	global_load_dword v21, v[4:5], off
	v_lshl_add_u64 v[4:5], v[4:5], 0, s[6:7]
	global_load_dword v22, v[4:5], off
	v_lshl_add_u64 v[4:5], v[4:5], 0, s[6:7]
	global_load_dword v23, v[4:5], off
	v_lshl_add_u64 v[4:5], v[4:5], 0, s[6:7]
	global_load_dword v24, v[4:5], off
	v_lshl_add_u64 v[4:5], v[4:5], 0, s[6:7]
	global_load_dword v25, v[4:5], off
	v_lshl_add_u64 v[4:5], v[4:5], 0, s[6:7]
	global_load_dword v26, v[4:5], off
	v_lshl_add_u64 v[4:5], v[4:5], 0, s[6:7]
	global_load_dword v27, v[4:5], off
	v_lshl_add_u64 v[4:5], v[4:5], 0, s[6:7]
	global_load_dword v28, v[4:5], off
	v_lshl_add_u64 v[4:5], v[4:5], 0, s[6:7]
	global_load_dword v29, v[4:5], off
	v_lshl_add_u64 v[4:5], v[4:5], 0, s[6:7]
	global_load_dword v30, v32, s[18:19]
	global_load_dword v31, v32, s[18:19] offset:2048
	s_waitcnt vmcnt(0)
; #define LAS __attribute__((address_space(3)))
; __device__ __forceinline__ float fast_rcp(float x) { return __builtin_amdgcn_rcpf(x); }
; __device__ __forceinline__ float fast_exp2(float x) { return __builtin_amdgcn_exp2f(x); }
; __device__ __forceinline__ float sigmoidf_(float x) { return fast_rcp(1.0f + fast_exp2(-x * LOG2E)); }
; __device__ __forceinline__ float siluf_(float x) { return x * sigmoidf_(x); }
; __device__ void phase_setup(const Params& p, LAS unsigned char* lds) {
;     ...
;         LAS float* sc = (LAS float*)lds;
;         __syncthreads();
;         for (int i = tid; i < 33 * D; i += 512) { const int r = i >> 10, k = i & 1023; const float v = (r < 32) ? p.in[I_C][r * D + k] : p.in[I_CCTX][k]; sc[i] = siluf_(v); }
;         __syncthreads();
	v_mul_f32_e32 v40, 0xbfb8aa3b, v10
	v_exp_f32_e32 v40, v40
	s_nop 0
	v_add_f32_e32 v40, 1.0, v40
	v_rcp_f32_e32 v40, v40
	s_nop 0
	v_mul_f32_e32 v10, v10, v40
	ds_write_b32 v6, v10
	v_add_u32_e32 v6, 0x800, v6
	v_mul_f32_e32 v40, 0xbfb8aa3b, v11
	v_exp_f32_e32 v40, v40
	s_nop 0
	v_add_f32_e32 v40, 1.0, v40
	v_rcp_f32_e32 v40, v40
	s_nop 0
	v_mul_f32_e32 v11, v11, v40
	ds_write_b32 v6, v11
	v_add_u32_e32 v6, 0x800, v6
	v_mul_f32_e32 v40, 0xbfb8aa3b, v12
	v_exp_f32_e32 v40, v40
	s_nop 0
	v_add_f32_e32 v40, 1.0, v40
	v_rcp_f32_e32 v40, v40
	s_nop 0
	v_mul_f32_e32 v12, v12, v40
	ds_write_b32 v6, v12
	v_add_u32_e32 v6, 0x800, v6
	v_mul_f32_e32 v40, 0xbfb8aa3b, v13
	v_exp_f32_e32 v40, v40
	s_nop 0
	v_add_f32_e32 v40, 1.0, v40
	v_rcp_f32_e32 v40, v40
	s_nop 0
	v_mul_f32_e32 v13, v13, v40
	ds_write_b32 v6, v13
	v_add_u32_e32 v6, 0x800, v6
	v_mul_f32_e32 v40, 0xbfb8aa3b, v14
	v_exp_f32_e32 v40, v40
	s_nop 0
	v_add_f32_e32 v40, 1.0, v40
	v_rcp_f32_e32 v40, v40
	s_nop 0
	v_mul_f32_e32 v14, v14, v40
	ds_write_b32 v6, v14
	v_add_u32_e32 v6, 0x800, v6
	v_mul_f32_e32 v40, 0xbfb8aa3b, v15
	v_exp_f32_e32 v40, v40
	s_nop 0
	v_add_f32_e32 v40, 1.0, v40
	v_rcp_f32_e32 v40, v40
	s_nop 0
	v_mul_f32_e32 v15, v15, v40
	ds_write_b32 v6, v15
	v_add_u32_e32 v6, 0x800, v6
	v_mul_f32_e32 v40, 0xbfb8aa3b, v16
	v_exp_f32_e32 v40, v40
	s_nop 0
	v_add_f32_e32 v40, 1.0, v40
	v_rcp_f32_e32 v40, v40
	s_nop 0
	v_mul_f32_e32 v16, v16, v40
	ds_write_b32 v6, v16
	v_add_u32_e32 v6, 0x800, v6
	v_mul_f32_e32 v40, 0xbfb8aa3b, v17
	v_exp_f32_e32 v40, v40
	s_nop 0
	v_add_f32_e32 v40, 1.0, v40
	v_rcp_f32_e32 v40, v40
	s_nop 0
	v_mul_f32_e32 v17, v17, v40
	ds_write_b32 v6, v17
	v_add_u32_e32 v6, 0x800, v6
	v_mul_f32_e32 v40, 0xbfb8aa3b, v18
	v_exp_f32_e32 v40, v40
	s_nop 0
	v_add_f32_e32 v40, 1.0, v40
	v_rcp_f32_e32 v40, v40
	s_nop 0
	v_mul_f32_e32 v18, v18, v40
	ds_write_b32 v6, v18
	v_add_u32_e32 v6, 0x800, v6
	v_mul_f32_e32 v40, 0xbfb8aa3b, v19
	v_exp_f32_e32 v40, v40
	s_nop 0
	v_add_f32_e32 v40, 1.0, v40
	v_rcp_f32_e32 v40, v40
	s_nop 0
	v_mul_f32_e32 v19, v19, v40
	ds_write_b32 v6, v19
	v_add_u32_e32 v6, 0x800, v6
	v_mul_f32_e32 v40, 0xbfb8aa3b, v20
	v_exp_f32_e32 v40, v40
	s_nop 0
	v_add_f32_e32 v40, 1.0, v40
	v_rcp_f32_e32 v40, v40
	s_nop 0
	v_mul_f32_e32 v20, v20, v40
	ds_write_b32 v6, v20
	v_add_u32_e32 v6, 0x800, v6
	v_mul_f32_e32 v40, 0xbfb8aa3b, v21
	v_exp_f32_e32 v40, v40
	s_nop 0
	v_add_f32_e32 v40, 1.0, v40
	v_rcp_f32_e32 v40, v40
	s_nop 0
	v_mul_f32_e32 v21, v21, v40
	ds_write_b32 v6, v21
	v_add_u32_e32 v6, 0x800, v6
	v_mul_f32_e32 v40, 0xbfb8aa3b, v22
	v_exp_f32_e32 v40, v40
	s_nop 0
	v_add_f32_e32 v40, 1.0, v40
	v_rcp_f32_e32 v40, v40
	s_nop 0
	v_mul_f32_e32 v22, v22, v40
	ds_write_b32 v6, v22
	v_add_u32_e32 v6, 0x800, v6
	v_mul_f32_e32 v40, 0xbfb8aa3b, v23
	v_exp_f32_e32 v40, v40
	s_nop 0
	v_add_f32_e32 v40, 1.0, v40
	v_rcp_f32_e32 v40, v40
	s_nop 0
	v_mul_f32_e32 v23, v23, v40
	ds_write_b32 v6, v23
	v_add_u32_e32 v6, 0x800, v6
	v_mul_f32_e32 v40, 0xbfb8aa3b, v24
	v_exp_f32_e32 v40, v40
	s_nop 0
	v_add_f32_e32 v40, 1.0, v40
	v_rcp_f32_e32 v40, v40
	s_nop 0
	v_mul_f32_e32 v24, v24, v40
	ds_write_b32 v6, v24
	v_add_u32_e32 v6, 0x800, v6
	v_mul_f32_e32 v40, 0xbfb8aa3b, v25
	v_exp_f32_e32 v40, v40
	s_nop 0
	v_add_f32_e32 v40, 1.0, v40
	v_rcp_f32_e32 v40, v40
	s_nop 0
	v_mul_f32_e32 v25, v25, v40
	ds_write_b32 v6, v25
	v_add_u32_e32 v6, 0x800, v6
	v_mul_f32_e32 v40, 0xbfb8aa3b, v26
	v_exp_f32_e32 v40, v40
	s_nop 0
	v_add_f32_e32 v40, 1.0, v40
	v_rcp_f32_e32 v40, v40
	s_nop 0
	v_mul_f32_e32 v26, v26, v40
	ds_write_b32 v6, v26
	v_add_u32_e32 v6, 0x800, v6
	v_mul_f32_e32 v40, 0xbfb8aa3b, v27
	v_exp_f32_e32 v40, v40
	s_nop 0
	v_add_f32_e32 v40, 1.0, v40
	v_rcp_f32_e32 v40, v40
	s_nop 0
	v_mul_f32_e32 v27, v27, v40
	ds_write_b32 v6, v27
	v_add_u32_e32 v6, 0x800, v6
	v_mul_f32_e32 v40, 0xbfb8aa3b, v28
	v_exp_f32_e32 v40, v40
	s_nop 0
	v_add_f32_e32 v40, 1.0, v40
	v_rcp_f32_e32 v40, v40
	s_nop 0
	v_mul_f32_e32 v28, v28, v40
	ds_write_b32 v6, v28
	v_add_u32_e32 v6, 0x800, v6
	v_mul_f32_e32 v40, 0xbfb8aa3b, v29
	v_exp_f32_e32 v40, v40
	s_nop 0
	v_add_f32_e32 v40, 1.0, v40
	v_rcp_f32_e32 v40, v40
	s_nop 0
	v_mul_f32_e32 v29, v29, v40
	ds_write_b32 v6, v29
	v_add_u32_e32 v6, 0x800, v6
	v_mul_f32_e32 v40, 0xbfb8aa3b, v30
	v_exp_f32_e32 v40, v40
	s_nop 0
	v_add_f32_e32 v40, 1.0, v40
	v_rcp_f32_e32 v40, v40
	s_nop 0
	v_mul_f32_e32 v30, v30, v40
	ds_write_b32 v6, v30
	v_add_u32_e32 v6, 0x800, v6
	v_mul_f32_e32 v40, 0xbfb8aa3b, v31
	v_exp_f32_e32 v40, v40
	s_nop 0
	v_add_f32_e32 v40, 1.0, v40
	v_rcp_f32_e32 v40, v40
	s_nop 0
	v_mul_f32_e32 v31, v31, v40
	ds_write_b32 v6, v31
	v_add_u32_e32 v6, 0x800, v6
